# optc2+qhoist: overlap P1 epilogue store drain with next unit first 3 phases; attention Q loads issued before bias-table wait
# baseline (speedup 1.0000x reference)
; #define LAS __attribute__((address_space(3)))
; __global__ void __launch_bounds__(NWAVES * 64, 2) skel_fwd(Args args) {
;     extern __shared__ __attribute__((aligned(16))) unsigned char lds[];
;     Frame F;
;     F.lds = (LAS unsigned char*)lds;
;     F.MISC = (volatile LAS unsigned*)(F.lds + MISC_OFF);
;     F.tid = threadIdx.x; F.lane = F.tid & 63; F.wave = __builtin_amdgcn_readfirstlane(F.tid >> 6);
;     F.G = gridDim.x; { const int bx = blockIdx.x; F.vcu = (F.G % 8 == 0) ? (bx % 8) * (F.G / 8) + bx / 8 : bx; }
_Z8skel_fwd4Args:
	s_mov_b32 s99, 0
	s_load_dword s33, s[0:1], 0xf0
	s_mov_b32 s89, s2
	s_add_u32 s2, s0, 0xf0
	s_addc_u32 s3, s1, 0
	v_readfirstlane_b32 s8, v0
	v_writelane_b32 v255, s2, 0
	s_mov_b32 s96, s89
	s_nop 0
	v_writelane_b32 v255, s3, 1
	s_waitcnt lgkmcnt(0)
	s_and_b32 s2, s33, 7
	s_cmp_lg_u32 s2, 0
	s_cbranch_scc1 .LBB0_2
	s_ashr_i32 s3, s89, 31
	s_lshr_b32 s3, s3, 29
	s_add_i32 s3, s89, s3
	s_and_b32 s4, s3, -8
	s_ashr_i32 s2, s33, 3
	s_sub_i32 s4, s89, s4
	s_mul_i32 s2, s2, s4
	s_ashr_i32 s3, s3, 3
	s_add_i32 s96, s2, s3

; #define PG8_STAGE(bufoff, gbase, voff) do { _Pragma("unroll") for (int _i = 0; _i < 2; ++_i) \
;         __builtin_amdgcn_global_load_lds((const unsigned*)((const char*)(gbase) + (voff)[_i]), (PG8_LAS unsigned*)(lds + (bufoff) + ldsw + _i * 8192), 16, 0, 0); } while (0)
; #define PG8_LDA(dst, b, h) do { _Pragma("unroll") for (int m = 0; m < 4; ++m) _Pragma("unroll") for (int k = 0; k < 2; ++k) dst[m][k] = *(const PG8_LAS bf16x8*)(lds + PG8_SA(b, h) + aoff + m * 2048 + k * 1024); } while (0)
; #define PG8_LDB(dst, b, h) do { _Pragma("unroll") for (int n = 0; n < 2; ++n) _Pragma("unroll") for (int k = 0; k < 2; ++k) dst[n][k] = *(const PG8_LAS bf16x8*)(lds + PG8_SB(b, h) + boff + n * 2048 + k * 1024); } while (0)
; #define PG8_MMA(ai, bj, At, Bt) do { __builtin_amdgcn_s_setprio(1); _Pragma("unroll") for (int m = 0; m < 4; ++m) _Pragma("unroll") for (int n = 0; n < 2; ++n) _Pragma("unroll") for (int k = 0; k < 2; ++k) \
;         acc[ai][bj][m][n] = __builtin_amdgcn_mfma_f32_16x16x32_bf16(Bt[n][k], At[m][k], acc[ai][bj][m][n], 0, 0, 0); __builtin_amdgcn_s_setprio(0); } while (0)
; #define PG8_WAIT_V(n) asm volatile("s_waitcnt vmcnt(" #n ")" ::: "memory")
; #define PG8_WAIT_L(n) asm volatile("s_waitcnt lgkmcnt(" #n ")" ::: "memory")
; #define PG8_BAR __builtin_amdgcn_s_barrier()
; #define PG8_SCHED __builtin_amdgcn_sched_barrier(0)
; template <class Epi, class Sched, bool ALIGN_EPI>
; __device__ __forceinline__ unsigned long long gemm_phase(PG8_LAS unsigned char* lds, const Gemm g, const Sched& S, const Epi& E, const int probe_id) {
;     ...
;             const bool last = (t == nt - 2);
;             const char* a1 = cA + (size_t)(t + 1) * kstep;
;             const char* a2 = last ? nA : cA + (size_t)(t + 2) * kstep; const char* b2 = last ? nB : cB + (size_t)(t + 2) * kstep;
;             const char* a3 = a2 + kstep; const char* b3 = b2 + kstep;
;             PG8_LDB(B0, 0, 0); PG8_LDB(B1, 0, 1); PG8_SCHED; PG8_LDA(At, 0, 0); PG8_STAGE(PG8_SA(1, 1), a1 + hstepA, voffA);
;             PG8_WAIT_V(8); PG8_WAIT_L(0); PG8_BAR; PG8_MMA(0, 0, At, B0); PG8_MMA(0, 1, At, B1); PG8_BAR; PG8_SCHED;
;             PG8_LDA(At, 0, 1); PG8_STAGE(PG8_SB(0, 0), b2, voffB); PG8_STAGE(PG8_SB(0, 1), b2 + hstepB, voffB); PG8_STAGE(PG8_SA(0, 0), a2, voffA);
.LBB0_127:
	ds_read_b128 v[130:133], v180
	ds_read_b128 v[134:137], v180 offset:1024
	ds_read_b128 v[138:141], v180 offset:2048
	ds_read_b128 v[142:145], v180 offset:3072
	ds_read_b128 v[164:167], v181
	ds_read_b128 v[168:171], v181 offset:1024
	ds_read_b128 v[172:175], v181 offset:2048
	ds_read_b128 v[188:191], v181 offset:3072
	s_add_u32 s8, s6, 0xfffc0080
	s_addc_u32 s9, s7, -1
	s_cmp_eq_u32 s76, 12
	s_cselect_b32 s11, s2, s9
	s_cselect_b32 s10, s5, s8
	s_cselect_b32 s9, s29, s71
	s_cselect_b32 s8, s56, s69
	v_lshl_add_u64 v[176:177], s[6:7], 0, v[158:159]
	s_add_i32 m0, s34, 0xc000
	ds_read_b128 v[192:195], v182
	ds_read_b128 v[196:199], v182 offset:1024
	ds_read_b128 v[200:203], v182 offset:2048
	ds_read_b128 v[204:207], v182 offset:3072
	ds_read_b128 v[208:211], v182 offset:4096
	ds_read_b128 v[212:215], v182 offset:5120
	ds_read_b128 v[216:219], v182 offset:6144
	ds_read_b128 v[220:223], v182 offset:7168
	s_cmp_lg_u32 s99, 0
	s_cbranch_scc1 .Lc2_p1skip
	global_load_lds_dwordx4 v[176:177], off
	v_lshl_add_u64 v[176:177], s[6:7], 0, v[160:161]
	s_add_i32 m0, s34, 0xe000
	s_nop 0
	global_load_lds_dwordx4 v[176:177], off
	s_waitcnt vmcnt(8)
.Lc2_p1skip:
	s_waitcnt lgkmcnt(0)
	s_barrier
	s_setprio 1
	s_waitcnt lgkmcnt(0)
	v_mfma_f32_16x16x32_bf16 v[126:129], v[130:133], v[192:195], v[126:129]
	v_mfma_f32_16x16x32_bf16 v[122:125], v[138:141], v[192:195], v[122:125]
	v_mfma_f32_16x16x32_bf16 v[110:113], v[130:133], v[200:203], v[110:113]
	v_mfma_f32_16x16x32_bf16 v[106:109], v[138:141], v[200:203], v[106:109]
	v_mfma_f32_16x16x32_bf16 v[94:97], v[130:133], v[208:211], v[94:97]
	v_mfma_f32_16x16x32_bf16 v[90:93], v[138:141], v[208:211], v[90:93]
	v_mfma_f32_16x16x32_bf16 v[78:81], v[130:133], v[216:219], v[78:81]
	v_mfma_f32_16x16x32_bf16 v[74:77], v[138:141], v[216:219], v[74:77]
	v_mfma_f32_16x16x32_bf16 v[126:129], v[134:137], v[196:199], v[126:129]
	v_mfma_f32_16x16x32_bf16 v[122:125], v[142:145], v[196:199], v[122:125]
	v_mfma_f32_16x16x32_bf16 v[110:113], v[134:137], v[204:207], v[110:113]
	v_mfma_f32_16x16x32_bf16 v[106:109], v[142:145], v[204:207], v[106:109]
	v_mfma_f32_16x16x32_bf16 v[94:97], v[134:137], v[212:215], v[94:97]
	v_mfma_f32_16x16x32_bf16 v[90:93], v[142:145], v[212:215], v[90:93]
	v_mfma_f32_16x16x32_bf16 v[78:81], v[134:137], v[220:223], v[78:81]
	v_mfma_f32_16x16x32_bf16 v[74:77], v[142:145], v[220:223], v[74:77]
	s_setprio 0
	s_setprio 1
	v_mfma_f32_16x16x32_bf16 v[118:121], v[164:167], v[192:195], v[118:121]
	v_mfma_f32_16x16x32_bf16 v[114:117], v[172:175], v[192:195], v[114:117]
	v_mfma_f32_16x16x32_bf16 v[102:105], v[164:167], v[200:203], v[102:105]
	v_mfma_f32_16x16x32_bf16 v[98:101], v[172:175], v[200:203], v[98:101]
	v_mfma_f32_16x16x32_bf16 v[86:89], v[164:167], v[208:211], v[86:89]
	v_mfma_f32_16x16x32_bf16 v[82:85], v[172:175], v[208:211], v[82:85]
	v_mfma_f32_16x16x32_bf16 v[70:73], v[164:167], v[216:219], v[70:73]
	v_mfma_f32_16x16x32_bf16 v[66:69], v[172:175], v[216:219], v[66:69]
	v_mfma_f32_16x16x32_bf16 v[118:121], v[168:171], v[196:199], v[118:121]
	v_mfma_f32_16x16x32_bf16 v[114:117], v[188:191], v[196:199], v[114:117]
	v_mfma_f32_16x16x32_bf16 v[102:105], v[168:171], v[204:207], v[102:105]
	v_mfma_f32_16x16x32_bf16 v[98:101], v[188:191], v[204:207], v[98:101]
	v_mfma_f32_16x16x32_bf16 v[86:89], v[168:171], v[212:215], v[86:89]
	v_mfma_f32_16x16x32_bf16 v[82:85], v[188:191], v[212:215], v[82:85]
	v_mfma_f32_16x16x32_bf16 v[70:73], v[168:171], v[220:223], v[70:73]
	v_mfma_f32_16x16x32_bf16 v[66:69], v[188:191], v[220:223], v[66:69]
	s_setprio 0
	s_barrier
	s_add_i32 s86, s57, s15
	v_lshl_add_u64 v[176:177], s[8:9], 0, v[150:151]
	s_mov_b32 m0, s86
	ds_read_b128 v[192:195], v182 offset:16384
	ds_read_b128 v[196:199], v182 offset:17408
	ds_read_b128 v[200:203], v182 offset:18432
	ds_read_b128 v[204:207], v182 offset:19456
	ds_read_b128 v[208:211], v182 offset:20480
	ds_read_b128 v[212:215], v182 offset:21504
	ds_read_b128 v[216:219], v182 offset:22528
	ds_read_b128 v[220:223], v182 offset:23552
	global_load_lds_dwordx4 v[176:177], off
	s_add_i32 m0, s86, 0x2000
	s_add_u32 s86, s8, 0x40000
	v_lshl_add_u64 v[224:225], s[8:9], 0, v[154:155]
	s_addc_u32 s87, s9, 0
	s_add_i32 s88, s60, s15
	global_load_lds_dwordx4 v[224:225], off
	v_lshl_add_u64 v[226:227], s[86:87], 0, v[150:151]
	s_mov_b32 m0, s88
	v_lshl_add_u64 v[228:229], s[10:11], 0, v[152:153]
	global_load_lds_dwordx4 v[226:227], off
	v_lshl_add_u64 v[226:227], s[86:87], 0, v[154:155]
	s_add_i32 m0, s88, 0x2000
	s_nop 0
	global_load_lds_dwordx4 v[226:227], off
	v_lshl_add_u64 v[226:227], s[10:11], 0, v[148:149]
	s_mov_b32 m0, s34
	s_nop 0
	global_load_lds_dwordx4 v[226:227], off
	s_mov_b32 m0, s35
	s_nop 0
	global_load_lds_dwordx4 v[228:229], off
	s_cmp_lg_u32 s99, 0
	s_cbranch_scc1 .Lc2_p2skip
	s_waitcnt vmcnt(8)
; #define PG8_STAGE(bufoff, gbase, voff) do { _Pragma("unroll") for (int _i = 0; _i < 2; ++_i) \
;         __builtin_amdgcn_global_load_lds((const unsigned*)((const char*)(gbase) + (voff)[_i]), (PG8_LAS unsigned*)(lds + (bufoff) + ldsw + _i * 8192), 16, 0, 0); } while (0)
; #define PG8_LDA(dst, b, h) do { _Pragma("unroll") for (int m = 0; m < 4; ++m) _Pragma("unroll") for (int k = 0; k < 2; ++k) dst[m][k] = *(const PG8_LAS bf16x8*)(lds + PG8_SA(b, h) + aoff + m * 2048 + k * 1024); } while (0)
; #define PG8_LDB(dst, b, h) do { _Pragma("unroll") for (int n = 0; n < 2; ++n) _Pragma("unroll") for (int k = 0; k < 2; ++k) dst[n][k] = *(const PG8_LAS bf16x8*)(lds + PG8_SB(b, h) + boff + n * 2048 + k * 1024); } while (0)
; #define PG8_MMA(ai, bj, At, Bt) do { __builtin_amdgcn_s_setprio(1); _Pragma("unroll") for (int m = 0; m < 4; ++m) _Pragma("unroll") for (int n = 0; n < 2; ++n) _Pragma("unroll") for (int k = 0; k < 2; ++k) \
;         acc[ai][bj][m][n] = __builtin_amdgcn_mfma_f32_16x16x32_bf16(Bt[n][k], At[m][k], acc[ai][bj][m][n], 0, 0, 0); __builtin_amdgcn_s_setprio(0); } while (0)
; #define PG8_WAIT_V(n) asm volatile("s_waitcnt vmcnt(" #n ")" ::: "memory")
; #define PG8_WAIT_L(n) asm volatile("s_waitcnt lgkmcnt(" #n ")" ::: "memory")
; #define PG8_BAR __builtin_amdgcn_s_barrier()
; #define PG8_SCHED __builtin_amdgcn_sched_barrier(0)
; template <class Epi, class Sched, bool ALIGN_EPI>
; __device__ __forceinline__ unsigned long long gemm_phase(PG8_LAS unsigned char* lds, const Gemm g, const Sched& S, const Epi& E, const int probe_id) {
;     ...
;             PG8_LDA(At, 0, 1); PG8_STAGE(PG8_SB(0, 0), b2, voffB); PG8_STAGE(PG8_SB(0, 1), b2 + hstepB, voffB); PG8_STAGE(PG8_SA(0, 0), a2, voffA);
;             PG8_WAIT_V(8); PG8_WAIT_L(0); PG8_BAR; PG8_MMA(1, 0, At, B0); PG8_MMA(1, 1, At, B1); PG8_BAR; PG8_SCHED;
;             PG8_LDB(B0, 1, 0); PG8_LDB(B1, 1, 1); PG8_SCHED; PG8_LDA(At, 1, 0); PG8_STAGE(PG8_SA(0, 1), a2 + hstepA, voffA);
;             PG8_WAIT_V(8); PG8_WAIT_L(0); PG8_BAR; PG8_MMA(0, 0, At, B0); PG8_MMA(0, 1, At, B1); PG8_BAR; PG8_SCHED;
.Lc2_p2skip:
	s_waitcnt lgkmcnt(0)
	s_barrier
	s_setprio 1
	s_waitcnt lgkmcnt(0)
	v_mfma_f32_16x16x32_bf16 v[62:65], v[130:133], v[192:195], v[62:65]
	v_mfma_f32_16x16x32_bf16 v[58:61], v[138:141], v[192:195], v[58:61]
	v_mfma_f32_16x16x32_bf16 v[46:49], v[130:133], v[200:203], v[46:49]
	v_mfma_f32_16x16x32_bf16 v[42:45], v[138:141], v[200:203], v[42:45]
	v_mfma_f32_16x16x32_bf16 v[30:33], v[130:133], v[208:211], v[30:33]
	v_mfma_f32_16x16x32_bf16 v[26:29], v[138:141], v[208:211], v[26:29]
	v_mfma_f32_16x16x32_bf16 v[14:17], v[130:133], v[216:219], v[14:17]
	v_mfma_f32_16x16x32_bf16 v[10:13], v[138:141], v[216:219], v[10:13]
	v_mfma_f32_16x16x32_bf16 v[62:65], v[134:137], v[196:199], v[62:65]
	v_mfma_f32_16x16x32_bf16 v[58:61], v[142:145], v[196:199], v[58:61]
	v_mfma_f32_16x16x32_bf16 v[46:49], v[134:137], v[204:207], v[46:49]
	v_mfma_f32_16x16x32_bf16 v[42:45], v[142:145], v[204:207], v[42:45]
	v_mfma_f32_16x16x32_bf16 v[30:33], v[134:137], v[212:215], v[30:33]
	v_mfma_f32_16x16x32_bf16 v[26:29], v[142:145], v[212:215], v[26:29]
	v_mfma_f32_16x16x32_bf16 v[14:17], v[134:137], v[220:223], v[14:17]
	v_mfma_f32_16x16x32_bf16 v[10:13], v[142:145], v[220:223], v[10:13]
	s_setprio 0
	s_setprio 1
	v_mfma_f32_16x16x32_bf16 v[54:57], v[164:167], v[192:195], v[54:57]
	v_mfma_f32_16x16x32_bf16 v[50:53], v[172:175], v[192:195], v[50:53]
	v_mfma_f32_16x16x32_bf16 v[38:41], v[164:167], v[200:203], v[38:41]
	v_mfma_f32_16x16x32_bf16 v[34:37], v[172:175], v[200:203], v[34:37]
	v_mfma_f32_16x16x32_bf16 v[22:25], v[164:167], v[208:211], v[22:25]
	v_mfma_f32_16x16x32_bf16 v[18:21], v[172:175], v[208:211], v[18:21]
	v_mfma_f32_16x16x32_bf16 v[6:9], v[164:167], v[216:219], v[6:9]
	v_mfma_f32_16x16x32_bf16 v[2:5], v[172:175], v[216:219], v[2:5]
	v_mfma_f32_16x16x32_bf16 v[54:57], v[168:171], v[196:199], v[54:57]
	v_mfma_f32_16x16x32_bf16 v[50:53], v[188:191], v[196:199], v[50:53]
	v_mfma_f32_16x16x32_bf16 v[38:41], v[168:171], v[204:207], v[38:41]
	v_mfma_f32_16x16x32_bf16 v[34:37], v[188:191], v[204:207], v[34:37]
	v_mfma_f32_16x16x32_bf16 v[22:25], v[168:171], v[212:215], v[22:25]
	v_mfma_f32_16x16x32_bf16 v[18:21], v[188:191], v[212:215], v[18:21]
	v_mfma_f32_16x16x32_bf16 v[6:9], v[168:171], v[220:223], v[6:9]
	v_mfma_f32_16x16x32_bf16 v[2:5], v[188:191], v[220:223], v[2:5]
	s_setprio 0
	s_barrier
	s_add_i32 s86, 0, 0x18000
	s_add_i32 s87, 0, 0x1c000
	v_add_u32_e32 v142, s86, v147
	v_add_u32_e32 v156, s87, v147
	ds_read_b128 v[130:133], v142
	ds_read_b128 v[134:137], v142 offset:1024
	ds_read_b128 v[138:141], v142 offset:2048
	ds_read_b128 v[142:145], v142 offset:3072
	ds_read_b128 v[164:167], v156
	ds_read_b128 v[168:171], v156 offset:1024
	ds_read_b128 v[172:175], v156 offset:2048
	ds_read_b128 v[188:191], v156 offset:3072
	s_add_u32 s10, s10, 0x40000
	s_addc_u32 s11, s11, 0
	s_mov_b32 m0, s77
	v_lshl_add_u64 v[230:231], s[10:11], 0, v[148:149]
	ds_read_b128 v[192:195], v182 offset:32768
	ds_read_b128 v[196:199], v182 offset:33792
	ds_read_b128 v[200:203], v182 offset:34816
	ds_read_b128 v[204:207], v182 offset:35840
	ds_read_b128 v[208:211], v182 offset:36864
	ds_read_b128 v[212:215], v182 offset:37888
	ds_read_b128 v[216:219], v182 offset:38912
	ds_read_b128 v[220:223], v182 offset:39936
	global_load_lds_dwordx4 v[230:231], off
	v_lshl_add_u64 v[230:231], s[10:11], 0, v[152:153]
	s_mov_b32 m0, s85
	s_nop 0
	global_load_lds_dwordx4 v[230:231], off
	s_cmp_lg_u32 s99, 0
	s_cbranch_scc1 .Lc2_p3skip
	s_waitcnt vmcnt(8)
.Lc2_p3skip:
	s_waitcnt lgkmcnt(0)
	s_barrier
	s_setprio 1
	s_waitcnt lgkmcnt(0)
	v_mfma_f32_16x16x32_bf16 v[126:129], v[130:133], v[192:195], v[126:129]
	v_mfma_f32_16x16x32_bf16 v[122:125], v[138:141], v[192:195], v[122:125]
	v_mfma_f32_16x16x32_bf16 v[110:113], v[130:133], v[200:203], v[110:113]
	v_mfma_f32_16x16x32_bf16 v[106:109], v[138:141], v[200:203], v[106:109]
	v_mfma_f32_16x16x32_bf16 v[94:97], v[130:133], v[208:211], v[94:97]
	v_mfma_f32_16x16x32_bf16 v[90:93], v[138:141], v[208:211], v[90:93]
	v_mfma_f32_16x16x32_bf16 v[78:81], v[130:133], v[216:219], v[78:81]
	v_mfma_f32_16x16x32_bf16 v[74:77], v[138:141], v[216:219], v[74:77]
	v_mfma_f32_16x16x32_bf16 v[126:129], v[134:137], v[196:199], v[126:129]
	v_mfma_f32_16x16x32_bf16 v[122:125], v[142:145], v[196:199], v[122:125]
	v_mfma_f32_16x16x32_bf16 v[110:113], v[134:137], v[204:207], v[110:113]
	v_mfma_f32_16x16x32_bf16 v[106:109], v[142:145], v[204:207], v[106:109]
	v_mfma_f32_16x16x32_bf16 v[94:97], v[134:137], v[212:215], v[94:97]
	v_mfma_f32_16x16x32_bf16 v[90:93], v[142:145], v[212:215], v[90:93]
	v_mfma_f32_16x16x32_bf16 v[78:81], v[134:137], v[220:223], v[78:81]
	v_mfma_f32_16x16x32_bf16 v[74:77], v[142:145], v[220:223], v[74:77]
	s_setprio 0
	s_setprio 1
	v_mfma_f32_16x16x32_bf16 v[118:121], v[164:167], v[192:195], v[118:121]
	v_mfma_f32_16x16x32_bf16 v[114:117], v[172:175], v[192:195], v[114:117]
	v_mfma_f32_16x16x32_bf16 v[102:105], v[164:167], v[200:203], v[102:105]
	v_mfma_f32_16x16x32_bf16 v[98:101], v[172:175], v[200:203], v[98:101]
	v_mfma_f32_16x16x32_bf16 v[86:89], v[164:167], v[208:211], v[86:89]
	v_mfma_f32_16x16x32_bf16 v[82:85], v[172:175], v[208:211], v[82:85]
	v_mfma_f32_16x16x32_bf16 v[70:73], v[164:167], v[216:219], v[70:73]
	v_mfma_f32_16x16x32_bf16 v[66:69], v[172:175], v[216:219], v[66:69]
	v_mfma_f32_16x16x32_bf16 v[118:121], v[168:171], v[196:199], v[118:121]
	v_mfma_f32_16x16x32_bf16 v[114:117], v[188:191], v[196:199], v[114:117]
	v_mfma_f32_16x16x32_bf16 v[102:105], v[168:171], v[204:207], v[102:105]
	v_mfma_f32_16x16x32_bf16 v[98:101], v[188:191], v[204:207], v[98:101]
	v_mfma_f32_16x16x32_bf16 v[86:89], v[168:171], v[212:215], v[86:89]
	v_mfma_f32_16x16x32_bf16 v[82:85], v[188:191], v[212:215], v[82:85]
	v_mfma_f32_16x16x32_bf16 v[70:73], v[168:171], v[220:223], v[70:73]
	v_mfma_f32_16x16x32_bf16 v[66:69], v[188:191], v[220:223], v[66:69]
	s_setprio 0
	s_barrier
; #define PG8_STAGE(bufoff, gbase, voff) do { _Pragma("unroll") for (int _i = 0; _i < 2; ++_i) \
;         __builtin_amdgcn_global_load_lds((const unsigned*)((const char*)(gbase) + (voff)[_i]), (PG8_LAS unsigned*)(lds + (bufoff) + ldsw + _i * 8192), 16, 0, 0); } while (0)
; #define PG8_LDA(dst, b, h) do { _Pragma("unroll") for (int m = 0; m < 4; ++m) _Pragma("unroll") for (int k = 0; k < 2; ++k) dst[m][k] = *(const PG8_LAS bf16x8*)(lds + PG8_SA(b, h) + aoff + m * 2048 + k * 1024); } while (0)
; #define PG8_MMA(ai, bj, At, Bt) do { __builtin_amdgcn_s_setprio(1); _Pragma("unroll") for (int m = 0; m < 4; ++m) _Pragma("unroll") for (int n = 0; n < 2; ++n) _Pragma("unroll") for (int k = 0; k < 2; ++k) \
;         acc[ai][bj][m][n] = __builtin_amdgcn_mfma_f32_16x16x32_bf16(Bt[n][k], At[m][k], acc[ai][bj][m][n], 0, 0, 0); __builtin_amdgcn_s_setprio(0); } while (0)
; #define PG8_WAIT_V(n) asm volatile("s_waitcnt vmcnt(" #n ")" ::: "memory")
; #define PG8_WAIT_L(n) asm volatile("s_waitcnt lgkmcnt(" #n ")" ::: "memory")
; #define PG8_BAR __builtin_amdgcn_s_barrier()
; #define PG8_SCHED __builtin_amdgcn_sched_barrier(0)
; template <class Epi, class Sched, bool ALIGN_EPI>
; __device__ __forceinline__ unsigned long long gemm_phase(PG8_LAS unsigned char* lds, const Gemm g, const Sched& S, const Epi& E, const int probe_id) {
;     ...
;             PG8_LDA(At, 1, 1); PG8_STAGE(PG8_SB(1, 0), b3, voffB); PG8_STAGE(PG8_SB(1, 1), b3 + hstepB, voffB); PG8_STAGE(PG8_SA(1, 0), a3, voffA);
;             PG8_WAIT_V(8); PG8_WAIT_L(0); PG8_BAR; PG8_MMA(1, 0, At, B0); PG8_MMA(1, 1, At, B1); PG8_BAR; PG8_SCHED;
;         }
;         if constexpr (ALIGN_EPI) { if (wr == 0) PG8_BAR; }
	s_add_i32 s10, s86, s15
	v_lshl_add_u64 v[176:177], v[176:177], 0, s[30:31]
	s_mov_b32 m0, s10
	ds_read_b128 v[192:195], v182 offset:49152
	ds_read_b128 v[196:199], v182 offset:50176
	ds_read_b128 v[200:203], v182 offset:51200
	ds_read_b128 v[204:207], v182 offset:52224
	ds_read_b128 v[208:211], v182 offset:53248
	ds_read_b128 v[212:215], v182 offset:54272
	ds_read_b128 v[216:219], v182 offset:55296
	ds_read_b128 v[220:223], v182 offset:56320
	global_load_lds_dwordx4 v[176:177], off
	s_add_i32 m0, s10, 0x2000
	s_add_u32 s8, s8, 0x40080
	v_lshl_add_u64 v[176:177], v[224:225], 0, s[30:31]
	s_addc_u32 s9, s9, 0
	s_add_i32 s10, s87, s15
	global_load_lds_dwordx4 v[176:177], off
	v_lshl_add_u64 v[176:177], s[8:9], 0, v[150:151]
	s_mov_b32 m0, s10
	s_nop 0
	global_load_lds_dwordx4 v[176:177], off
	v_lshl_add_u64 v[176:177], s[8:9], 0, v[154:155]
	s_add_i32 m0, s10, 0x2000
	s_nop 0
	global_load_lds_dwordx4 v[176:177], off
	v_lshl_add_u64 v[176:177], v[226:227], 0, s[30:31]
	s_mov_b32 m0, s95
	s_nop 0
	global_load_lds_dwordx4 v[176:177], off
	v_lshl_add_u64 v[176:177], v[228:229], 0, s[30:31]
	s_mov_b32 m0, s97
	s_nop 0
	global_load_lds_dwordx4 v[176:177], off
	s_mov_b32 s99, 0
	s_waitcnt vmcnt(8)
	s_waitcnt lgkmcnt(0)
	s_barrier
	s_setprio 1
	s_waitcnt lgkmcnt(0)
	v_mfma_f32_16x16x32_bf16 v[62:65], v[130:133], v[192:195], v[62:65]
	v_mfma_f32_16x16x32_bf16 v[58:61], v[138:141], v[192:195], v[58:61]
	v_mfma_f32_16x16x32_bf16 v[46:49], v[130:133], v[200:203], v[46:49]
	v_mfma_f32_16x16x32_bf16 v[42:45], v[138:141], v[200:203], v[42:45]
	v_mfma_f32_16x16x32_bf16 v[30:33], v[130:133], v[208:211], v[30:33]
	v_mfma_f32_16x16x32_bf16 v[26:29], v[138:141], v[208:211], v[26:29]
	v_mfma_f32_16x16x32_bf16 v[14:17], v[130:133], v[216:219], v[14:17]
	v_mfma_f32_16x16x32_bf16 v[10:13], v[138:141], v[216:219], v[10:13]
	v_mfma_f32_16x16x32_bf16 v[62:65], v[134:137], v[196:199], v[62:65]
	v_mfma_f32_16x16x32_bf16 v[58:61], v[142:145], v[196:199], v[58:61]
	v_mfma_f32_16x16x32_bf16 v[46:49], v[134:137], v[204:207], v[46:49]
	v_mfma_f32_16x16x32_bf16 v[42:45], v[142:145], v[204:207], v[42:45]
	v_mfma_f32_16x16x32_bf16 v[30:33], v[134:137], v[212:215], v[30:33]
	v_mfma_f32_16x16x32_bf16 v[26:29], v[142:145], v[212:215], v[26:29]
	v_mfma_f32_16x16x32_bf16 v[14:17], v[134:137], v[220:223], v[14:17]
	v_mfma_f32_16x16x32_bf16 v[10:13], v[142:145], v[220:223], v[10:13]
	s_setprio 0
	s_setprio 1
	v_mfma_f32_16x16x32_bf16 v[54:57], v[164:167], v[192:195], v[54:57]
	v_mfma_f32_16x16x32_bf16 v[50:53], v[172:175], v[192:195], v[50:53]
	v_mfma_f32_16x16x32_bf16 v[38:41], v[164:167], v[200:203], v[38:41]
	v_mfma_f32_16x16x32_bf16 v[34:37], v[172:175], v[200:203], v[34:37]
	v_mfma_f32_16x16x32_bf16 v[22:25], v[164:167], v[208:211], v[22:25]
	v_mfma_f32_16x16x32_bf16 v[18:21], v[172:175], v[208:211], v[18:21]
	v_mfma_f32_16x16x32_bf16 v[6:9], v[164:167], v[216:219], v[6:9]
	v_mfma_f32_16x16x32_bf16 v[2:5], v[172:175], v[216:219], v[2:5]
	v_mfma_f32_16x16x32_bf16 v[54:57], v[168:171], v[196:199], v[54:57]
	v_mfma_f32_16x16x32_bf16 v[50:53], v[188:191], v[196:199], v[50:53]
	v_mfma_f32_16x16x32_bf16 v[38:41], v[168:171], v[204:207], v[38:41]
	v_mfma_f32_16x16x32_bf16 v[34:37], v[188:191], v[204:207], v[34:37]
	v_mfma_f32_16x16x32_bf16 v[22:25], v[168:171], v[212:215], v[22:25]
	v_mfma_f32_16x16x32_bf16 v[18:21], v[188:191], v[212:215], v[18:21]
	v_mfma_f32_16x16x32_bf16 v[6:9], v[168:171], v[220:223], v[6:9]
	v_mfma_f32_16x16x32_bf16 v[2:5], v[188:191], v[220:223], v[2:5]
	s_setprio 0
	s_barrier
	s_add_i32 s76, s76, 2
	s_add_u32 s6, s6, 0x100
	s_addc_u32 s7, s7, 0
	s_add_u32 s69, s69, 0x100
	s_addc_u32 s71, s71, 0
	s_cmp_gt_u32 s76, 13
	s_cbranch_scc0 .LBB0_127
	s_and_b64 vcc, exec, s[50:51]
	s_cbranch_vccz .LBB0_130
	s_barrier
; #define GAS __attribute__((address_space(1)))
; __device__ __forceinline__ float sigm(float v) { return __builtin_amdgcn_rcpf(1.f + __builtin_amdgcn_exp2f(-LOG2E * v)); }
;     __device__ __forceinline__ bool operator()(pg8::f32x4 (&acc)[2][2][4][2], const pg8::Unit& u, int wr, int wc, int fr, int fq) const {
;         const int g = u.pn >> 2;
;         const int cb = (u.pn & 3) * 256 + wc * 64 + fq * 8;
;         const int row0 = u.pm * 256 + wr * 64 + fr;
;         const bool smp = u.pm >= 256;
;         if (g == 2 || g == 3) {
;     ...
;         bf16* dstb = (bf16*)(ws + (g == 0 ? WS_XA : g == 1 ? WS_ZA : g == 4 ? WS_V : WS_ZB));
;         float* vout = smp ? out + O_VS - (size_t)MP * DM : out + O_VP;
; #pragma unroll
;         for (int ai = 0; ai < 2; ++ai)
; #pragma unroll
;             for (int m = 0; m < 4; ++m) {
;                 const int rowi = row0 + ai * 128 + m * 16; const size_t row = (size_t)rowi;
; #pragma unroll
;                 for (int bj = 0; bj < 2; ++bj) {
;                     float v[8];
; #pragma unroll
;                     for (int e = 0; e < 8; ++e) v[e] = acc[ai][bj][m][e >> 2][e & 3];
;                     if (g == 0) {
;                         const int t = smp ? (rowi & 63) : (rowi & 2047); const int T = smp ? 64 : 2048;
;                         if (t >= T - 3) { const int b = smp ? ((rowi - MP) >> 6) : (rowi >> 11);
;                             GAS f32x4* o = (GAS f32x4*)(out + (smp ? O_CS : O_CP) + (size_t)(b * 3 + (t - (T - 3))) * DM + cb + bj * 32);
;                             o[0] = (f32x4){v[0], v[1], v[2], v[3]}; o[1] = (f32x4){v[4], v[5], v[6], v[7]}; }
;                     } else if (g == 4) {
;                         GAS f32x4* o = (GAS f32x4*)(vout + row * DM + cb + bj * 32); o[0] = (f32x4){v[0], v[1], v[2], v[3]}; o[1] = (f32x4){v[4], v[5], v[6], v[7]};
;                     } else if (g == 1 || g == 5) {
; #pragma unroll
;                         for (int e = 0; e < 8; ++e) v[e] = v[e] * sigm(v[e]);
.LBB0_130:
	s_add_u32 s100, s5, 0x40080
	s_addc_u32 s101, s2, 0
	v_lshl_add_u64 v[232:233], s[100:101], 0, v[158:159]
	s_add_i32 m0, s34, 0xc000
	s_nop 0
	global_load_lds_dwordx4 v[232:233], off
	v_lshl_add_u64 v[232:233], s[100:101], 0, v[160:161]
	s_add_i32 m0, s34, 0xe000
	s_nop 0
	global_load_lds_dwordx4 v[232:233], off
	s_lshl_b32 s2, s84, 8
	s_lshl_b32 s56, s4, 8
	s_ashr_i32 s29, s84, 2
	s_and_b32 s2, s2, 0x300
	s_add_i32 s56, s56, s92
	s_cmpk_gt_i32 s4, 0xff
	v_or_b32_e32 v172, s2, v179
	s_cselect_b64 s[4:5], -1, 0
	s_and_b32 s2, s84, -8
	v_or_b32_e32 v164, s56, v1
	s_cmp_lg_u32 s2, 8
	s_mov_b64 s[6:7], -1
	s_cbranch_scc0 .LBB0_312
	s_cmp_lt_i32 s29, 6
	s_cbranch_scc0 .LBB0_309
	s_cmp_lt_u32 s84, 4
	s_cselect_b64 s[8:9], -1, 0
	s_cmp_gt_u32 s84, 3
	s_cselect_b64 s[6:7], -1, 0
	s_cmp_eq_u32 s29, 4
	s_cselect_b64 s[90:91], -1, 0
	s_cmp_lg_u32 s29, 4
	s_cselect_b64 s[88:89], -1, 0
	s_and_b64 s[10:11], s[4:5], exec
	s_mov_b32 s2, 0x21080000
	s_cselect_b32 s2, s2, 0x20800000
	s_add_u32 s10, s72, s2
	s_addc_u32 s11, s73, 0
	s_and_b32 s2, s84, 0xffffffec
	s_cmp_eq_u32 s2, 4
	v_lshlrev_b32_e32 v130, 2, v172
	v_mov_b32_e32 v131, v157
	s_cselect_b64 s[86:87], -1, 0
	v_lshl_add_u64 v[132:133], s[10:11], 0, v[130:131]
	s_and_b64 s[10:11], s[4:5], exec
	s_movk_i32 s2, 0xffc3
	s_cselect_b32 s94, s2, 0xfffff803
	s_mov_b32 s2, 0xc620000
	s_cselect_b32 s71, 63, 0x7ff
	s_cselect_b32 s76, 61, 0x7fd
	s_cselect_b32 s69, s2, 0xc200000
	s_add_i32 s2, s56, 0xffff0000
	s_mov_b64 s[0:1], s[50:51]
	s_mov_b32 s50, s92
	s_ashr_i32 s2, s2, 6
	s_ashr_i32 s92, s56, 11
	v_ashrrev_i32_e32 v165, 31, v164
	s_and_b64 s[10:11], s[4:5], exec
	v_lshlrev_b64 v[134:135], 12, v[164:165]
	v_and_b32_e32 v131, s71, v164
	s_mov_b32 s14, s13
	s_mov_b32 s13, s12
	s_mov_b32 s12, s3
	s_mov_b32 s3, s93
	s_cselect_b32 s2, s2, s92
	v_lshl_add_u64 v[136:137], v[132:133], 0, v[134:135]
	v_cmp_le_u32_e64 s[10:11], s76, v131
	s_mov_b64 s[92:93], -1
	s_and_b64 vcc, exec, s[6:7]
	s_cbranch_vccz .LBB0_139
	s_and_b64 vcc, exec, s[88:89]
	s_cbranch_vccz .LBB0_136
	s_andn2_b64 vcc, exec, s[86:87]
	s_cbranch_vccnz .LBB0_348
	v_mul_f32_e32 v134, 0xbfb8aa3b, v126
	v_mul_f32_e32 v135, 0xbfb8aa3b, v127
	v_mul_f32_e32 v138, 0xbfb8aa3b, v128
	v_mul_f32_e32 v139, 0xbfb8aa3b, v129
	v_mul_f32_e32 v140, 0xbfb8aa3b, v122
	v_mul_f32_e32 v141, 0xbfb8aa3b, v123
	v_mul_f32_e32 v142, 0xbfb8aa3b, v124
	v_mul_f32_e32 v143, 0xbfb8aa3b, v125
	v_exp_f32_e32 v134, v134
	v_exp_f32_e32 v135, v135
	v_exp_f32_e32 v138, v138
	v_exp_f32_e32 v139, v139
	v_exp_f32_e32 v140, v140
	v_exp_f32_e32 v141, v141
	v_exp_f32_e32 v142, v142
	v_exp_f32_e32 v143, v143
	v_add_f32_e32 v134, 1.0, v134
	v_add_f32_e32 v135, 1.0, v135
	v_add_f32_e32 v138, 1.0, v138
	v_add_f32_e32 v139, 1.0, v139
	v_add_f32_e32 v140, 1.0, v140
	v_add_f32_e32 v141, 1.0, v141
	v_add_f32_e32 v142, 1.0, v142
	v_add_f32_e32 v143, 1.0, v143
	v_rcp_f32_e32 v134, v134
	v_rcp_f32_e32 v135, v135
	v_rcp_f32_e32 v138, v138
	v_rcp_f32_e32 v139, v139
	v_rcp_f32_e32 v140, v140
	v_rcp_f32_e32 v142, v142
	v_rcp_f32_e32 v143, v143
	v_rcp_f32_e32 v141, v141
	v_pk_mul_f32 v[144:145], v[128:129], v[138:139]
	v_pk_mul_f32 v[168:169], v[126:127], v[134:135]
	v_pk_mul_f32 v[142:143], v[124:125], v[142:143]
	v_pk_mul_f32 v[166:167], v[122:123], v[140:141]
	s_cbranch_execz .LBB0_137
	s_branch .LBB0_138

; #define PG8_BAR __builtin_amdgcn_s_barrier()
; template <class Epi, class Sched, bool ALIGN_EPI>
; __device__ __forceinline__ unsigned long long gemm_phase(PG8_LAS unsigned char* lds, const Gemm g, const Sched& S, const Epi& E, const int probe_id) {
;     ...
;         const bool keep = E(acc, cur, wr, wc, fr, fq);
;         if (PROBE_TS == 5 && probe_id == 1 && blockIdx.x == 0) pacc += __builtin_amdgcn_s_memrealtime() - pt1;
;         if (PROBE_TS == 6 && probe_id == 1 && blockIdx.x == 0 && (cur.pn >> 2) == 4) pacc += __builtin_amdgcn_s_memrealtime() - pt0;
;         if (!has_next) break;
;         if (!keep) {
; #pragma unroll
;         for (int a = 0; a < 2; ++a)
; #pragma unroll
;             for (int b = 0; b < 2; ++b)
; #pragma unroll
;                 for (int m = 0; m < 4; ++m)
; #pragma unroll
;                     for (int n = 0; n < 2; ++n) acc[a][b][m][n] = (f32x4){0.f, 0.f, 0.f, 0.f};
;         }
;         cur = nxt; cA = nA; cB = nB; ++ui;
;         if constexpr (ALIGN_EPI) { if (wr == 1) PG8_BAR; }
.LBB0_345:
	s_waitcnt vmcnt(16)
	s_mov_b32 s99, 1
	s_andn2_b64 vcc, exec, s[78:79]
	s_mov_b64 s[4:5], -1
	s_cbranch_vccnz .LBB0_116
	v_readlane_b32 s4, v255, 12
	v_readlane_b32 s5, v255, 13
	s_andn2_b64 vcc, exec, s[4:5]
	s_cbranch_vccnz .LBB0_115
	s_barrier
	s_branch .LBB0_115

; #define PTS_BEGIN(id, cond) do { if (PROBE_TS == (id) && blockIdx.x == 0 && (cond)) F.pt0 = __builtin_amdgcn_s_memrealtime(); } while (0)
; #define GAS __attribute__((address_space(1)))
; __device__ __forceinline__ int v_rd_base(int lane) { return ((lane & 3) << 3) | (((lane >> 2) & 3) << 6) | (((lane >> 4) & 1) << 5) | (((lane >> 5) & 1) << 8); }
; __device__ __forceinline__ void attn_prompt(Frame& F, int b, int h, int qb, float lam, float mshift) {
;     ...
;     const bf16* Kt = (const bf16*)(F.ws + WS_K) + ((size_t)b * SEQ) * DM + h * 128; const bf16* Vt = (const bf16*)(F.ws + WS_V) + ((size_t)b * SEQ) * DM + h * 128;
;     int ko[2], vo[2];
; #pragma unroll
;     for (int q = 0; q < 2; ++q) {
;         const int row = 8 * w + 4 * q + (lane >> 4), cpos = lane & 15; ko[q] = row * DM + 8 * (cpos ^ (row & 7));
;         const int c = w * 128 + q * 64 + lane, st = c >> 5, rowk = (c >> 2) & 7, cc = c & 3, kk = (st >> 2) * 8 + rowk, col = (st & 3) * 32 + cc * 8;
;         const int k = (kk & ~0xC) | ((kk & 4) << 1) | ((kk & 8) >> 1); vo[q] = k * DM + col; }
;     const unsigned lds0 = (unsigned)(uintptr_t)L;
;     const unsigned dK = lds0 + w * 2048, dV = lds0 + 16384 + w * 2048;
;     ...
;     PTS_BEGIN(1, qb == 15 && F.pacc == 0); PTS_BEGIN(3, qb == 15 && F.pacc == 0);
;     DMA_TILE(0, 0); DMA_TILE(1, P_SLOT);
;     if (tid < 255) TB[tid] = F.in[17][rel_bucket(tid - 191) * NH + h] * LOG2E - __builtin_bit_cast(float, F.MISC[17]);
;     bf16x8 qr[4];
;     { const bf16* Qw = QB + (qrow0 + 32 * rb + r32) * DM + h * 128 + m * 64 + hi * 8;
; #pragma unroll
;       for (int d0 = 0; d0 < 4; ++d0) qr[d0] = *(const GAS bf16x8*)(Qw + d0 * 16); }
;     const int vbase = (int)lds0 + 16384 + v_rd_base(lane);
;     f32x16 o[4]; f32x16 ol;
;     const bf16x8 ones = {0x3F80, 0x3F80, 0x3F80, 0x3F80, 0x3F80, 0x3F80, 0x3F80, 0x3F80};
; #pragma unroll
;     for (int d = 0; d < 4; ++d)
; #pragma unroll
;         for (int r = 0; r < 16; ++r) o[d][r] = 0.f;
; #pragma unroll
;     for (int r = 0; r < 16; ++r) ol[r] = 0.f;
;     f32x16 pA0, pA1, pB0, pB1; bf16x8 pa0, pa1, pa2, pa3; f32x16 CF;
.LBB0_496:
	s_andn2_b64 vcc, exec, s[0:1]
	s_mov_b64 s[0:1], -1
	s_cbranch_vccnz .LBB0_449
	s_ashr_i32 s52, s2, 3
	v_mov_b32_e32 v219, v0
	s_and_b32 s2, s2, 7
	s_ashr_i32 s53, s52, 31
	v_lshrrev_b32_e32 v4, 2, v219
	v_lshlrev_b32_e32 v5, 3, v219
	v_lshrrev_b32_e32 v6, 1, v219
	s_lshl_b32 s10, s2, 7
	s_lshl_b64 s[0:1], s[52:53], 22
	v_and_b32_e32 v5, 24, v5
	v_and_or_b32 v4, v4, 3, s88
	v_and_b32_e32 v6, 8, v6
	s_add_u32 s3, s85, s0
	v_bfe_u32 v2, v219, 4, 2
	v_and_or_b32 v5, v219, 32, v5
	v_or3_b32 v4, v4, v6, s89
	s_addc_u32 s14, s86, s1
	v_lshl_or_b32 v196, v4, 10, v5
	v_bitop3_b32 v5, v2, v219, 15 bitop3:0x78
	v_and_b32_e32 v3, 15, v219
	v_or_b32_e32 v4, s87, v2
	v_lshlrev_b32_e32 v5, 3, v5
	s_add_u32 s0, s90, s0
	v_lshl_or_b32 v4, v4, 10, v5
	v_or_b32_e32 v5, 4, v2
	v_bitop3_b32 v2, v2, v3, 4 bitop3:0x36
	s_addc_u32 s1, s91, s1
	s_lshl_b32 s34, s2, 8
	v_or_b32_e32 v5, s87, v5
	v_lshlrev_b32_e32 v2, 3, v2
	s_add_u32 s0, s0, s34
	v_lshl_or_b32 v5, v5, 10, v2
	s_addc_u32 s1, s1, 0
	v_lshlrev_b32_e32 v210, 1, v4
	s_add_u32 s56, s3, s34
	v_lshl_add_u64 v[2:3], s[0:1], 0, v[210:211]
	s_mov_b32 s3, m0
	s_mov_b32 m0, s92
	s_nop 0
	global_load_lds_dwordx4 v[2:3], off
	s_mov_b32 m0, s3
	v_lshlrev_b32_e32 v198, 1, v5
	v_mov_b32_e32 v199, v211
	s_addc_u32 s57, s14, 0
	v_lshl_add_u64 v[2:3], s[0:1], 0, v[198:199]
	s_add_i32 s3, s92, 0x400
	s_mov_b32 s14, m0
	s_mov_b32 m0, s3
	s_nop 0
	global_load_lds_dwordx4 v[2:3], off
	s_mov_b32 m0, s14
	v_mov_b32_e32 v197, v211
	v_lshl_add_u64 v[2:3], v[196:197], 1, s[56:57]
	s_mov_b32 s3, m0
	s_mov_b32 m0, s93
	s_nop 0
	global_load_lds_dwordx4 v[2:3], off
	s_mov_b32 m0, s3
	s_add_i32 s3, s93, 0x400
	s_add_u32 s54, s0, 0x20000
	v_lshl_add_u64 v[4:5], v[2:3], 0, s[50:51]
	s_mov_b32 s14, m0
	s_mov_b32 m0, s3
	s_nop 0
	global_load_lds_dwordx4 v[4:5], off
	s_mov_b32 m0, s14
	s_addc_u32 s55, s1, 0
	v_lshl_add_u64 v[4:5], s[54:55], 0, v[210:211]
	s_add_i32 s3, s92, 0x8000
	s_mov_b32 s14, m0
	s_mov_b32 m0, s3
	s_nop 0
	global_load_lds_dwordx4 v[4:5], off
	s_mov_b32 m0, s14
	v_lshl_add_u64 v[4:5], s[54:55], 0, v[198:199]
	s_add_i32 s3, s92, 0x8400
	s_mov_b32 s14, m0
	s_mov_b32 m0, s3
	s_nop 0
	global_load_lds_dwordx4 v[4:5], off
	s_mov_b32 m0, s14
	s_mov_b64 s[54:55], 0x20000
	v_lshl_add_u64 v[4:5], v[2:3], 0, s[54:55]
	s_add_i32 s3, s93, 0x8000
	s_mov_b32 s14, m0
	s_mov_b32 m0, s3
	s_nop 0
	global_load_lds_dwordx4 v[4:5], off
	s_mov_b32 m0, s14
	s_mov_b64 s[54:55], 0x20080
	v_lshl_add_u64 v[2:3], v[2:3], 0, s[54:55]
	s_add_i32 s3, s93, 0x8400
	s_mov_b32 s14, m0
	s_mov_b32 m0, s3
	s_nop 0
	global_load_lds_dwordx4 v[2:3], off
	s_mov_b32 m0, s14
	s_lshl_b32 s34, s58, 1
	s_lshl_b32 s14, s58, 7
	s_lshl_b64 s[52:53], s[52:53], 11
	v_and_b32_e32 v217, 31, v219
	s_add_u32 s52, s52, s14
	s_addc_u32 s53, s53, 0
	v_or_b32_e32 v2, s76, v217
	v_or_b32_e32 v2, s52, v2
	v_mov_b32_e32 v3, s53
	v_lshlrev_b64 v[2:3], 11, v[2:3]
	v_and_b32_e32 v218, 63, v219
	v_lshl_add_u64 v[2:3], s[24:25], 0, v[2:3]
	s_lshl_b32 s54, s10, 1
	s_mov_b32 s55, s11
	v_lshrrev_b32_e32 v216, 5, v218
	v_lshl_add_u64 v[2:3], v[2:3], 0, s[54:55]
	s_lshl_b32 s10, s69, 1
	v_lshl_add_u64 v[2:3], v[2:3], 0, s[10:11]
	s_waitcnt vmcnt(16)
	v_lshlrev_b32_e32 v194, 4, v216
	v_mov_b32_e32 v195, v211
	v_lshl_add_u64 v[2:3], v[2:3], 0, v[194:195]
	global_load_dwordx4 v[174:177], v[2:3], off
	global_load_dwordx4 v[170:173], v[2:3], off offset:32
	global_load_dwordx4 v[166:169], v[2:3], off offset:64
	global_load_dwordx4 v[162:165], v[2:3], off offset:96
	v_cmp_gt_i32_e32 vcc, s71, v219
	s_and_saveexec_b64 s[64:65], vcc
	s_cbranch_execz .LBB0_499
	v_add_u32_e32 v2, 0xffffff41, v219
	v_sub_u32_e32 v3, 0, v2
	v_max_i32_e32 v3, v2, v3
	v_mul_lo_u32 v2, v2, v2
	v_ffbh_u32_e32 v2, v2
	v_sub_u32_e32 v2, 33, v2
	v_min_u32_e32 v2, 15, v2
	v_cmp_gt_u32_e32 vcc, 8, v3
	s_movk_i32 s3, 0xbf
	v_lshl_add_u32 v4, v219, 2, 0
	v_cndmask_b32_e32 v2, v2, v3, vcc
	v_cmp_lt_i32_e32 vcc, s3, v219
	s_nop 1
	v_cndmask_b32_e64 v3, 0, 16, vcc
	v_add_u32_e32 v2, v2, v3
	v_lshl_or_b32 v2, v2, 3, s2
	v_mov_b32_e32 v3, v211
	v_lshl_add_u64 v[2:3], v[2:3], 2, s[38:39]
	global_load_dword v2, v[2:3], off
	v_mov_b32_e32 v3, s13
	ds_read_b32 v3, v3
	s_mov_b32 s2, 0x3fb8aa3b
	s_waitcnt vmcnt(0) lgkmcnt(0)
	v_fma_f32 v2, v2, s2, -v3
	v_add_u32_e32 v3, 0x20400, v4
	ds_write_b32 v3, v2
.LBB0_499:
	s_or_b64 exec, exec, s[64:65]
	s_or_b32 s3, s76, s14
	s_or_b32 s2, s34, 1
	s_cmp_gt_i32 s58, 0
	s_cselect_b64 s[58:59], -1, 0
	s_and_b64 s[60:61], s[58:59], exec
	s_cselect_b32 s60, 2, s2
	s_mov_b32 s61, s11
	s_lshl_b64 s[60:61], s[60:61], 17
	s_add_u32 s64, s0, s60
	v_mov_b32_e32 v2, s95
	s_addc_u32 s65, s1, s61
	s_waitcnt vmcnt(0)
	s_waitcnt lgkmcnt(0)
	s_barrier
	ds_read_b32 v82, v2
	s_add_u32 s60, s56, s60
	v_lshl_add_u64 v[2:3], s[64:65], 0, v[210:211]
	s_addc_u32 s61, s57, s61
	s_add_i32 s55, s92, 0x10000
	s_mov_b32 s66, m0
	s_mov_b32 m0, s55
	s_nop 0
	global_load_lds_dwordx4 v[2:3], off
	s_mov_b32 m0, s66
	v_lshl_add_u64 v[2:3], s[64:65], 0, v[198:199]
	s_add_i32 s55, s92, 0x10400
	s_mov_b32 s64, m0
	s_mov_b32 m0, s55
	s_nop 0
	global_load_lds_dwordx4 v[2:3], off
	s_mov_b32 m0, s64
	v_lshl_add_u64 v[2:3], v[196:197], 1, s[60:61]
	s_add_i32 s55, s93, 0x10000
	s_mov_b32 s60, m0
	s_mov_b32 m0, s55
	s_nop 0
	global_load_lds_dwordx4 v[2:3], off
	s_mov_b32 m0, s60
	v_lshl_add_u64 v[2:3], v[2:3], 0, s[50:51]
	s_add_i32 s55, s93, 0x10400
	s_mov_b32 s60, m0
	s_mov_b32 m0, s55
	s_nop 0
	global_load_lds_dwordx4 v[2:3], off
	s_mov_b32 m0, s60
	v_lshlrev_b32_e32 v2, 4, v219
	v_or_b32_e32 v42, s10, v194
	v_lshlrev_b32_e32 v195, 8, v217
	v_and_b32_e32 v43, 0x70, v2
	v_xad_u32 v200, v42, v43, v195
	v_add_u32_e32 v2, 0, v200
	ds_read_b128 v[38:41], v2
	ds_read_b128 v[34:37], v2 offset:8192
	s_waitcnt lgkmcnt(2)
	v_mov_b32_e32 v83, v82
	v_mov_b32_e32 v84, v82
	v_mov_b32_e32 v85, v82
	v_mov_b32_e32 v86, v82
	v_mov_b32_e32 v87, v82
	v_mov_b32_e32 v88, v82
	v_mov_b32_e32 v89, v82
	v_mov_b32_e32 v90, v82
	v_mov_b32_e32 v91, v82
	v_mov_b32_e32 v92, v82
	v_mov_b32_e32 v93, v82
	v_mov_b32_e32 v94, v82
	v_mov_b32_e32 v95, v82
	v_mov_b32_e32 v96, v82
	v_mov_b32_e32 v97, v82
	s_cmpk_gt_u32 s3, 0xbf
	s_mov_b64 s[60:61], -1
	s_cbranch_scc0 .LBB0_501
	s_waitcnt vmcnt(3) lgkmcnt(1)
	v_mfma_f32_32x32x16_bf16 v[2:17], v[38:41], v[174:177], v[82:97]
	s_mov_b64 s[60:61], 0
	s_waitcnt lgkmcnt(0)
	v_mfma_f32_32x32x16_bf16 v[18:33], v[34:37], v[174:177], v[82:97]

; __global__ void __launch_bounds__(NWAVES * 64, 2) skel_fwd(Args args) {
	.amdhsa_kernel _Z8skel_fwd4Args
		.amdhsa_group_segment_fixed_size 0
		.amdhsa_private_segment_fixed_size 0
		.amdhsa_kernarg_size 496
		.amdhsa_user_sgpr_count 2
		.amdhsa_user_sgpr_dispatch_ptr 0
		.amdhsa_user_sgpr_queue_ptr 0
		.amdhsa_user_sgpr_kernarg_segment_ptr 1
		.amdhsa_user_sgpr_dispatch_id 0
		.amdhsa_user_sgpr_kernarg_preload_length 0
		.amdhsa_user_sgpr_kernarg_preload_offset 0
		.amdhsa_user_sgpr_private_segment_size 0
		.amdhsa_uses_dynamic_stack 0
		.amdhsa_enable_private_segment 0
		.amdhsa_system_sgpr_workgroup_id_x 1
		.amdhsa_system_sgpr_workgroup_id_y 0
		.amdhsa_system_sgpr_workgroup_id_z 0
		.amdhsa_system_sgpr_workgroup_info 0
		.amdhsa_system_vgpr_workitem_id 0
		.amdhsa_next_free_vgpr 256
		.amdhsa_next_free_sgpr 102
		.amdhsa_accum_offset 256
		.amdhsa_reserve_vcc 1
		.amdhsa_float_round_mode_32 0
		.amdhsa_float_round_mode_16_64 0
		.amdhsa_float_denorm_mode_32 3
		.amdhsa_float_denorm_mode_16_64 3
		.amdhsa_dx10_clamp 1
		.amdhsa_ieee_mode 1
		.amdhsa_fp16_overflow 0
		.amdhsa_tg_split 0
		.amdhsa_exception_fp_ieee_invalid_op 0
		.amdhsa_exception_fp_denorm_src 0
		.amdhsa_exception_fp_ieee_div_zero 0
		.amdhsa_exception_fp_ieee_overflow 0
		.amdhsa_exception_fp_ieee_underflow 0
		.amdhsa_exception_fp_ieee_inexact 0
		.amdhsa_exception_int_div_zero 0
	.end_amdhsa_kernel

; __global__ void __launch_bounds__(NWAVES * 64, 2) skel_fwd(Args args) {
amdhsa.kernels:
  - .agpr_count:     0
    .args:
      - .offset:         0
        .size:           240
        .value_kind:     by_value
      - .offset:         240
        .size:           4
        .value_kind:     hidden_block_count_x
      - .offset:         244
        .size:           4
        .value_kind:     hidden_block_count_y
      - .offset:         248
        .size:           4
        .value_kind:     hidden_block_count_z
      - .offset:         252
        .size:           2
        .value_kind:     hidden_group_size_x
      - .offset:         254
        .size:           2
        .value_kind:     hidden_group_size_y
      - .offset:         256
        .size:           2
        .value_kind:     hidden_group_size_z
      - .offset:         258
        .size:           2
        .value_kind:     hidden_remainder_x
      - .offset:         260
        .size:           2
        .value_kind:     hidden_remainder_y
      - .offset:         262
        .size:           2
        .value_kind:     hidden_remainder_z
      - .offset:         280
        .size:           8
        .value_kind:     hidden_global_offset_x
      - .offset:         288
        .size:           8
        .value_kind:     hidden_global_offset_y
      - .offset:         296
        .size:           8
        .value_kind:     hidden_global_offset_z
      - .offset:         304
        .size:           2
        .value_kind:     hidden_grid_dims
      - .offset:         360
        .size:           4
        .value_kind:     hidden_dynamic_lds_size
    .group_segment_fixed_size: 0
    .kernarg_segment_align: 8
    .kernarg_segment_size: 496
    .language:       OpenCL C
    .language_version:
      - 2
      - 0
    .max_flat_workgroup_size: 512
    .name:           _Z8skel_fwd4Args
    .private_segment_fixed_size: 0
    .sgpr_count:     108
    .sgpr_spill_count: 37
    .symbol:         _Z8skel_fwd4Args.kd
    .uniform_work_group_size: 1
    .uses_dynamic_stack: false
    .vgpr_count:     256
    .vgpr_spill_count: 0
    .wavefront_size: 64
